# attention: K/V tiles double-buffered in LDS, one workgroup barrier per key chunk instead of two
# speedup vs baseline: 1.0070x; 1.0070x over previous
.LBB0_1054:
	s_or_b64 exec, exec, s[4:5]
	v_mov_b32_e32 v0, s48
	s_waitcnt lgkmcnt(0)
	s_barrier
	ds_read_b32 v0, v0
	s_waitcnt lgkmcnt(0)
	v_cmp_lt_i32_e32 vcc, 63, v0
	v_readfirstlane_b32 s4, v0
	s_cbranch_vccnz .LBB0_1073
	s_mov_b64 s[82:83], s[0:1]
	v_mov_b32_e32 v100, v226
	s_load_dwordx2 s[50:51], s[82:83], 0x58
	s_and_b32 s5, s4, 1
	s_lshl_b32 s4, s4, 1
	s_and_b32 s4, s4, -4
	v_readlane_b32 s6, v254, 14
	s_sub_i32 s4, 0x7c, s4
	s_or_b32 s6, s5, s6
	v_readlane_b32 s5, v254, 13
	s_or_b32 s5, s4, s5
	s_waitcnt lgkmcnt(0)
	s_add_u32 s56, s50, 0xb400000
	s_addc_u32 s57, s51, 0
	s_bfe_u32 s9, s4, 0x50002
	v_readfirstlane_b32 s4, v100
	s_ashr_i32 s7, s4, 8
	s_lshl_b32 s22, s6, 1
	s_add_i32 s8, s7, s22
	v_and_b32_e32 v28, 15, v100
	s_lshl_b32 s5, s5, 4
	s_lshr_b32 s4, s4, 2
	s_lshl_b32 s8, s8, 7
	s_and_b32 s23, s5, 0xfffff800
	s_lshl_b32 s5, s9, 6
	v_and_or_b32 v127, s4, 48, v28
	s_add_i32 s4, s8, 0x800
	s_or_b32 s5, s5, s23
	s_ashr_i32 s4, s4, 7
	v_or_b32_e32 v96, s5, v127
	s_ashr_i32 s5, s4, 31
	s_lshl_b64 s[4:5], s[4:5], 21
	v_ashrrev_i32_e32 v18, 5, v100
	v_ashrrev_i32_e32 v97, 31, v96
	s_add_u32 s4, s56, s4
	v_add_u32_e32 v16, s23, v18
	v_bfe_u32 v29, v100, 4, 2
	s_addc_u32 s5, s57, s5
	v_lshlrev_b64 v[98:99], 8, v[96:97]
	v_ashrrev_i32_e32 v17, 31, v16
	v_lshl_add_u64 v[0:1], s[4:5], 0, v[98:99]
	v_lshlrev_b32_e32 v208, 4, v29
	v_and_b32_e32 v19, 16, v100
	v_lshlrev_b64 v[16:17], 8, v[16:17]
	s_lshl_b32 s4, s6, 22
	v_lshl_add_u64 v[12:13], v[0:1], 0, v[208:209]
	v_lshl_add_u64 v[16:17], s[56:57], 0, v[16:17]
	v_lshl_or_b32 v208, v19, 17, s4
	v_lshlrev_b32_e32 v19, 4, v100
	v_lshl_add_u64 v[16:17], v[16:17], 0, v[208:209]
	v_and_b32_e32 v208, 0xf0, v19
	v_lshl_add_u64 v[16:17], v[16:17], 0, v[208:209]
	v_ashrrev_i32_e32 v19, 3, v100
	s_ashr_i32 s4, s23, 6
	v_lshl_add_u64 v[102:103], v[16:17], 0, s[62:63]
	v_lshl_add_u32 v16, s6, 8, v19
	s_ashr_i32 s5, s4, 31
	v_add_u32_e32 v16, 0x400, v16
	s_lshl_b64 s[4:5], s[4:5], 18
	v_lshlrev_b32_e32 v21, 3, v100
	v_ashrrev_i32_e32 v17, 31, v16
	s_add_u32 s4, s50, s4
	v_and_b32_e32 v22, 56, v21
	s_addc_u32 s5, s51, s5
	v_lshlrev_b64 v[16:17], 7, v[16:17]
	v_lshl_add_u64 v[16:17], s[4:5], 0, v[16:17]
	v_lshlrev_b32_e32 v208, 1, v22
	v_lshl_add_u64 v[16:17], v[16:17], 0, v[208:209]
	v_lshl_add_u64 v[104:105], v[16:17], 0, s[64:65]
	v_mul_lo_u32 v16, v19, s49
	v_add_lshl_u32 v31, v16, v22, 1
	v_lshlrev_b32_e32 v16, 2, v100
	v_sub_u32_e64 v20, s9, 8 clamp
	v_and_b32_e32 v16, 64, v16
	v_add_u32_e32 v16, v16, v18
	v_lshlrev_b32_e32 v208, 18, v20
	v_mul_lo_u32 v56, v16, s28
	v_lshl_add_u64 v[16:17], v[104:105], 0, v[208:209]
	v_add_co_u32_e32 v18, vcc, s21, v16
	v_lshlrev_b32_e32 v208, 14, v20
	v_readfirstlane_b32 s31, v20
	v_and_b32_e32 v57, 0x78, v21
	v_addc_co_u32_e32 v19, vcc, 0, v17, vcc
	v_lshl_add_u64 v[20:21], v[102:103], 0, v[208:209]
	v_add_co_u32_e32 v22, vcc, s35, v20
	global_load_dwordx4 v[0:3], v[12:13], off
	global_load_dwordx4 v[4:7], v[12:13], off offset:64
	global_load_dwordx4 v[8:11], v[12:13], off offset:128
	s_nop 0
	global_load_dwordx4 v[12:15], v[12:13], off offset:192
	v_addc_co_u32_e32 v23, vcc, 0, v21, vcc
	v_add_co_u32_e32 v24, vcc, s20, v16
	s_mul_i32 s4, s7, 0x410
	s_nop 0
	v_addc_co_u32_e32 v25, vcc, 0, v17, vcc
	v_add_co_u32_e32 v26, vcc, s17, v20
	s_add_i32 s38, s4, 0
	s_nop 0
	v_addc_co_u32_e32 v27, vcc, 0, v21, vcc
	global_load_dwordx4 v[52:55], v[24:25], off
	global_load_dwordx4 v[48:51], v[26:27], off
	v_add_co_u32_e32 v24, vcc, s17, v16
	v_lshlrev_b32_e32 v30, 3, v29
	s_nop 0
	v_addc_co_u32_e32 v25, vcc, 0, v17, vcc
	v_add_co_u32_e32 v26, vcc, s34, v20
	s_or_b32 s84, s12, s22
	s_nop 0
	v_addc_co_u32_e32 v27, vcc, 0, v21, vcc
	global_load_dwordx4 v[44:47], v[24:25], off
	global_load_dwordx4 v[40:43], v[26:27], off
	global_load_dwordx4 v[64:67], v[18:19], off
	global_load_dwordx4 v[32:35], v[16:17], off
	global_load_dwordx4 v[60:63], v[22:23], off
	global_load_dwordx4 v[36:39], v[20:21], off
	v_and_b32_e32 v19, 64, v233
	v_xor_b32_e32 v18, 16, v233
	v_add_u32_e32 v19, 64, v19
	v_cmp_lt_i32_e64 s[4:5], v18, v19
	v_max_i32_e32 v20, 2, v100
	v_sub_u32_e32 v20, v20, v100
	v_cndmask_b32_e64 v18, v233, v18, s[4:5]
	v_lshlrev_b32_e32 v126, 2, v18
	v_xor_b32_e32 v18, 32, v233
	v_cmp_lt_i32_e64 s[4:5], v18, v19
	v_add_u32_e32 v20, 0x1ff, v20
	v_lshl_or_b32 v17, s7, 6, v28
	v_cndmask_b32_e64 v18, v233, v18, s[4:5]
	v_lshrrev_b32_e32 v21, 9, v20
	v_mul_lo_u32 v17, v17, s28
	v_lshlrev_b32_e32 v125, 2, v18
	v_lshl_or_b32 v18, s7, 7, v28
	v_add_u32_e32 v21, 1, v21
	v_add_lshl_u32 v16, v56, v57, 1
	v_cmp_lt_i32_e32 vcc, s24, v100
	v_add_lshl_u32 v17, v17, v30, 1
	v_mul_lo_u32 v18, v18, s16
	v_add_u32_e32 v19, 0, v30
	v_lshlrev_b32_e32 v208, 2, v29
	v_and_b32_e32 v129, 0xfffffe, v21
	v_mov_b32_e32 v135, 0
	s_mov_b32 s42, s76
	s_add_i32 s38, s38, 0x23000
	s_mov_b32 s85, s13
	v_not_b32_e32 v128, v208
	v_or_b32_e32 v124, 16, v208
	v_or_b32_e32 v123, 32, v208
	v_or_b32_e32 v122, 48, v208
	v_cmp_lt_u32_e64 s[4:5], s61, v20
	v_lshl_add_u32 v130, v129, 9, v100
	s_mov_b32 s86, s84
	s_mov_b32 s87, s13
	s_mov_b32 s88, s84
	s_mov_b32 s89, s13
	v_add_u32_e32 v101, 0x200, v100
	v_cmp_ne_u32_e64 s[6:7], v21, v129
	v_mov_b32_e32 v136, 0xf149f2ca
	v_add_u32_e32 v131, 0, v16
	v_add_u32_e32 v132, 0, v31
	s_xor_b64 s[90:91], vcc, -1
	v_add_u32_e32 v133, 0, v17
	v_add_u32_e32 v134, v19, v18
	v_and_b32_e32 v149, 15, v100
	v_add_u32_e32 v149, 4, v149
	v_bfe_u32 v149, v149, 3, 1
	v_bfe_u32 v150, v100, 4, 2
	v_xor_b32_e32 v151, v150, v149
	v_lshlrev_b32_e32 v151, 4, v151
	v_lshlrev_b32_e32 v150, 3, v150
	v_sub_u32_e32 v151, v151, v150
	v_add_u32_e32 v134, v134, v151
	v_and_b32_e32 v149, 7, v100
	v_lshlrev_b32_e32 v150, 4, v149
	v_sub_u32_e32 v132, v132, v150
	v_and_b32_e32 v150, 4, v149
	v_lshl_add_u32 v132, v150, 4, v132
	v_and_b32_e32 v150, 1, v149
	v_lshl_add_u32 v132, v150, 5, v132
	v_and_b32_e32 v150, 2, v149
	v_lshl_add_u32 v132, v150, 2, v132
	v_bfe_u32 v150, v100, 3, 4
	v_add_u32_e32 v150, 4, v150
	v_bfe_u32 v150, v150, 3, 1
	v_lshlrev_b32_e32 v150, 4, v150
	v_sub_u32_e32 v148, 16, v150
	v_add_u32_e32 v148, v148, v132
	v_add_u32_e32 v132, v132, v150
	s_mov_b32 s32, 0x11800
	s_mov_b32 s39, s31
	v_mov_b32_e32 v20, 0
	v_mov_b32_e32 v21, v135
	v_mov_b32_e32 v22, v135
	v_mov_b32_e32 v23, v135
	v_mov_b32_e32 v28, 0
	v_mov_b32_e32 v29, v135
	v_mov_b32_e32 v30, v135
	v_mov_b32_e32 v31, v135
	v_mov_b32_e32 v16, 0
	v_mov_b32_e32 v17, v135
	v_mov_b32_e32 v18, v135
	v_mov_b32_e32 v19, v135
	v_mov_b32_e32 v56, 0
	v_mov_b32_e32 v57, v135
	v_mov_b32_e32 v58, v135
	v_mov_b32_e32 v59, v135
	v_mov_b32_e32 v68, 0
	v_mov_b32_e32 v69, v135
	v_mov_b32_e32 v70, v135
	v_mov_b32_e32 v71, v135
	v_mov_b32_e32 v72, 0
	v_mov_b32_e32 v73, v135
	v_mov_b32_e32 v74, v135
	v_mov_b32_e32 v75, v135
	v_mov_b32_e32 v24, 0
	v_mov_b32_e32 v25, v135
	v_mov_b32_e32 v26, v135
	v_mov_b32_e32 v27, v135
	v_mov_b32_e32 v76, 0
	v_mov_b32_e32 v77, v135
	v_mov_b32_e32 v78, v135
	v_mov_b32_e32 v79, v135
.LBB0_1056:
	s_cmp_eq_u32 s39, s31
	s_cselect_b64 s[22:23], -1, 0
	s_and_b64 s[22:23], s[90:91], s[22:23]
	s_waitcnt vmcnt(0)
	ds_write_b128 v131, v[36:39]
	ds_write_b64 v132, v[32:33] offset:34816
	ds_write_b64 v148, v[34:35] offset:34816
	ds_write_b128 v131, v[40:43] offset:4352
	ds_write_b64 v132, v[44:45] offset:44032
	ds_write_b64 v148, v[46:47] offset:44032
	ds_write_b128 v131, v[48:51] offset:8704
	ds_write_b64 v132, v[52:53] offset:53248
	ds_write_b64 v148, v[54:55] offset:53248
	ds_write_b128 v131, v[60:63] offset:13056
	ds_write_b64 v132, v[64:65] offset:62464
	ds_write_b64 v148, v[66:67] offset:62464
	s_and_saveexec_b64 s[76:77], s[22:23]
	s_cbranch_execz .LBB0_1064
	s_load_dwordx2 s[92:93], s[82:83], 0x48
	s_mov_b64 s[22:23], -1
	v_mov_b32_e32 v80, v100
	s_and_saveexec_b64 s[94:95], s[4:5]
	s_cbranch_execz .LBB0_1061
	s_mov_b64 s[96:97], 0
	v_mov_b32_e32 v82, v129
	v_mov_b64_e32 v[80:81], v[100:101]
.LBB0_1059:
	v_mul_hi_i32 v83, v80, s18
	v_lshrrev_b32_e32 v84, 31, v83
	v_ashrrev_i32_e32 v83, 7, v83
	v_add_u32_e32 v84, v83, v84
	v_mul_hi_i32 v83, v81, s18
	v_lshrrev_b32_e32 v85, 31, v83
	v_ashrrev_i32_e32 v83, 7, v83
	v_add_u32_e32 v86, v83, v85
	v_lshl_add_u32 v85, v84, 8, v84
	v_sub_u32_e32 v88, v80, v85
	v_ashrrev_i32_e32 v85, 31, v84
	v_ashrrev_i32_e32 v87, 31, v86
	v_lshl_add_u64 v[94:95], s[86:87], 0, v[84:85]
	s_waitcnt lgkmcnt(0)
	v_mov_b64_e32 v[106:107], s[92:93]
	v_lshl_add_u32 v83, v86, 8, v86
	v_lshl_add_u64 v[92:93], s[88:89], 0, v[86:87]
	v_mad_u64_u32 v[108:109], s[22:23], v94, s19, v[106:107]
	v_sub_u32_e32 v90, v81, v83
	v_ashrrev_i32_e32 v89, 31, v88
	v_mad_i32_i24 v109, v95, s19, v109
	v_mad_u64_u32 v[94:95], s[22:23], v92, s19, v[106:107]
	v_ashrrev_i32_e32 v91, 31, v90
	v_mad_i32_i24 v95, v93, s19, v95
	v_lshl_add_u64 v[92:93], v[88:89], 2, v[108:109]
	v_lshl_add_u64 v[94:95], v[90:91], 2, v[94:95]
	global_load_dword v92, v[92:93], off
	s_nop 0
	global_load_dword v93, v[94:95], off
	v_add_u32_e32 v82, -2, v82
	v_mul_lo_u32 v84, v84, s29
	s_add_i32 s22, 0, 0x23000
	v_lshlrev_b32_e32 v85, 2, v88
	v_cmp_eq_u32_e32 vcc, 0, v82
	v_mul_lo_u32 v83, v86, s29
	v_add3_u32 v84, s22, v84, v85
	v_lshlrev_b32_e32 v85, 2, v90
	v_add_u32_e32 v81, 0x400, v81
	v_add_u32_e32 v80, 0x400, v80
	s_or_b64 s[96:97], vcc, s[96:97]
	v_add3_u32 v83, s22, v83, v85
	s_waitcnt vmcnt(0)
	v_pk_mul_f32 v[92:93], v[92:93], s[60:61] op_sel_hi:[1,0]
	ds_write_b32 v84, v92
	ds_write_b32 v83, v93
	s_andn2_b64 exec, exec, s[96:97]
	s_cbranch_execnz .LBB0_1059
	s_or_b64 exec, exec, s[96:97]
	s_orn2_b64 s[22:23], s[6:7], exec
	v_mov_b32_e32 v80, v130
.LBB0_1061:
	s_or_b64 exec, exec, s[94:95]
	s_and_b64 exec, exec, s[22:23]
	s_cbranch_execz .LBB0_1064
	s_add_i32 s22, 0, 0x23000
	v_lshl_add_u32 v81, v80, 2, s22
	s_mov_b64 s[22:23], 0

.LBB0_1070:
	s_nop 1
	ds_bpermute_b32 v80, v126, v137
	v_max_f32_e32 v81, v137, v137
	s_waitcnt lgkmcnt(0)
	v_max_f32_e32 v80, v80, v80
	v_max_f32_e32 v80, v81, v80
	ds_bpermute_b32 v81, v125, v80
	s_waitcnt lgkmcnt(0)
	v_max3_f32 v88, v136, v80, v81
	v_sub_f32_e32 v80, v136, v88
	v_exp_f32_e32 v90, v80
	v_sub_f32_e32 v80, v120, v88
	v_exp_f32_e32 v80, v80
	v_sub_f32_e32 v82, v121, v88
	v_exp_f32_e32 v82, v82
	v_sub_f32_e32 v83, v112, v88
	v_exp_f32_e32 v83, v83
	v_sub_f32_e32 v84, v113, v88
	v_exp_f32_e32 v84, v84
	v_sub_f32_e32 v85, v108, v88
	v_fma_f32 v81, v135, v90, v80
	v_exp_f32_e32 v85, v85
	v_sub_f32_e32 v86, v109, v88
	v_add_f32_e32 v81, v82, v81
	v_exp_f32_e32 v86, v86
	v_sub_f32_e32 v87, v106, v88
	v_add_f32_e32 v81, v83, v81
	v_exp_f32_e32 v87, v87
	v_sub_f32_e32 v89, v107, v88
	v_add_f32_e32 v81, v84, v81
	v_exp_f32_e32 v89, v89
	v_add_f32_e32 v81, v85, v81
	v_add_f32_e32 v81, v86, v81
	v_add_f32_e32 v81, v87, v81
	v_add_f32_e32 v91, v89, v81
	v_cvt_pk_bf16_f32 v81, v83, v84
	v_sub_f32_e32 v84, v110, v88
	v_cvt_pk_bf16_f32 v83, v87, v89
	v_exp_f32_e32 v89, v84
	v_sub_f32_e32 v84, v111, v88
	v_exp_f32_e32 v92, v84
	v_sub_f32_e32 v84, v114, v88
	v_exp_f32_e32 v93, v84
	v_sub_f32_e32 v84, v115, v88
	v_exp_f32_e32 v94, v84
	v_sub_f32_e32 v84, v116, v88
	v_exp_f32_e32 v95, v84
	v_sub_f32_e32 v84, v117, v88
	v_exp_f32_e32 v106, v84
	v_sub_f32_e32 v84, v118, v88
	v_exp_f32_e32 v107, v84
	v_sub_f32_e32 v84, v119, v88
	v_exp_f32_e32 v135, v84
	v_cvt_pk_bf16_f32 v84, v89, v92
	v_add_f32_e32 v89, v89, v91
	v_add_f32_e32 v89, v92, v89
	v_add_f32_e32 v89, v93, v89
	v_add_f32_e32 v89, v94, v89
	v_add_f32_e32 v89, v95, v89
	v_cvt_pk_bf16_f32 v80, v80, v82
	v_cvt_pk_bf16_f32 v82, v85, v86
	v_cvt_pk_bf16_f32 v85, v93, v94
	v_add_f32_e32 v89, v106, v89
	v_add_u32_e32 v94, 0x8800, v134
	v_cvt_pk_bf16_f32 v86, v95, v106
	v_cvt_pk_bf16_f32 v87, v107, v135
	v_pk_mul_f32 v[74:75], v[74:75], v[90:91] op_sel_hi:[1,0]
	v_pk_mul_f32 v[72:73], v[72:73], v[90:91] op_sel_hi:[1,0]
	v_pk_mul_f32 v[70:71], v[70:71], v[90:91] op_sel_hi:[1,0]
	v_pk_mul_f32 v[68:69], v[68:69], v[90:91] op_sel_hi:[1,0]
	v_pk_mul_f32 v[58:59], v[58:59], v[90:91] op_sel_hi:[1,0]
	v_pk_mul_f32 v[56:57], v[56:57], v[90:91] op_sel_hi:[1,0]
	v_pk_mul_f32 v[18:19], v[18:19], v[90:91] op_sel_hi:[1,0]
	v_pk_mul_f32 v[16:17], v[16:17], v[90:91] op_sel_hi:[1,0]
	v_pk_mul_f32 v[30:31], v[30:31], v[90:91] op_sel_hi:[1,0]
	v_pk_mul_f32 v[28:29], v[28:29], v[90:91] op_sel_hi:[1,0]
	v_pk_mul_f32 v[22:23], v[22:23], v[90:91] op_sel_hi:[1,0]
	v_pk_mul_f32 v[20:21], v[20:21], v[90:91] op_sel_hi:[1,0]
	v_pk_mul_f32 v[26:27], v[26:27], v[90:91] op_sel_hi:[1,0]
	v_pk_mul_f32 v[24:25], v[24:25], v[90:91] op_sel_hi:[1,0]
	v_pk_mul_f32 v[78:79], v[78:79], v[90:91] op_sel_hi:[1,0]
	v_pk_mul_f32 v[76:77], v[76:77], v[90:91] op_sel_hi:[1,0]
	v_add_f32_e32 v89, v107, v89
	ds_read_b128 v[90:93], v94
	ds_read_b128 v[106:109], v94 offset:64
	v_add_u32_e32 v94, 0x9000, v134
	ds_read_b128 v[110:113], v94 offset:256
	ds_read_b128 v[114:117], v94 offset:320
	v_add_u32_e32 v94, 0x9800, v134
	ds_read_b128 v[118:121], v94 offset:512
	ds_read_b128 v[136:139], v94 offset:576
	v_add_u32_e32 v94, 0xa000, v134
	ds_read_b128 v[140:143], v94 offset:768
	ds_read_b128 v[144:147], v94 offset:832
	s_waitcnt lgkmcnt(7)
	v_mfma_f32_16x16x32_bf16 v[72:75], v[90:93], v[80:83], v[72:75]
	s_waitcnt lgkmcnt(5)
	v_mfma_f32_16x16x32_bf16 v[68:71], v[110:113], v[80:83], v[68:71]
	s_waitcnt lgkmcnt(3)
	v_mfma_f32_16x16x32_bf16 v[56:59], v[118:121], v[80:83], v[56:59]
	s_waitcnt lgkmcnt(1)
	v_mfma_f32_16x16x32_bf16 v[16:19], v[140:143], v[80:83], v[16:19]
	v_mfma_f32_16x16x32_bf16 v[72:75], v[106:109], v[84:87], v[72:75]
	v_mfma_f32_16x16x32_bf16 v[68:71], v[114:117], v[84:87], v[68:71]
	v_mfma_f32_16x16x32_bf16 v[56:59], v[136:139], v[84:87], v[56:59]
	s_waitcnt lgkmcnt(0)
	v_mfma_f32_16x16x32_bf16 v[16:19], v[144:147], v[84:87], v[16:19]
	v_add_u32_e32 v94, 0xa800, v134
	ds_read_b128 v[90:93], v94 offset:1024
	ds_read_b128 v[106:109], v94 offset:1088
	v_add_u32_e32 v94, 0xb000, v134
	ds_read_b128 v[110:113], v94 offset:1280
	ds_read_b128 v[114:117], v94 offset:1344
	v_add_u32_e32 v94, 0xb800, v134
	ds_read_b128 v[118:121], v94 offset:1536
	ds_read_b128 v[136:139], v94 offset:1600
	v_add_u32_e32 v94, 0xc000, v134
	ds_read_b128 v[140:143], v94 offset:1792
	ds_read_b128 v[144:147], v94 offset:1856
	s_waitcnt lgkmcnt(7)
	v_mfma_f32_16x16x32_bf16 v[28:31], v[90:93], v[80:83], v[28:31]
	s_waitcnt lgkmcnt(5)
	v_mfma_f32_16x16x32_bf16 v[20:23], v[110:113], v[80:83], v[20:23]
	s_waitcnt lgkmcnt(3)
	v_mfma_f32_16x16x32_bf16 v[24:27], v[118:121], v[80:83], v[24:27]
	s_waitcnt lgkmcnt(1)
	v_mfma_f32_16x16x32_bf16 v[76:79], v[140:143], v[80:83], v[76:79]
	v_mfma_f32_16x16x32_bf16 v[28:31], v[106:109], v[84:87], v[28:31]
	v_mfma_f32_16x16x32_bf16 v[20:23], v[114:117], v[84:87], v[20:23]
	v_mfma_f32_16x16x32_bf16 v[24:27], v[136:139], v[84:87], v[24:27]
	s_waitcnt lgkmcnt(0)
	v_mfma_f32_16x16x32_bf16 v[76:79], v[144:147], v[84:87], v[76:79]
	v_add_f32_e32 v135, v135, v89
	s_andn2_b64 vcc, exec, s[76:77]
	s_add_i32 s39, s39, 1
	s_cbranch_vccz .LBB0_1072
	v_mov_b32_e32 v136, v88
	v_add_u32_e32 v131, s32, v131
	v_add_u32_e32 v132, s32, v132
	v_add_u32_e32 v148, s32, v148
	v_add_u32_e32 v133, s32, v133
	v_add_u32_e32 v134, s32, v134
	s_sub_i32 s32, 0, s32
	s_branch .LBB0_1056

.LBB0_1108:
	s_or_b64 exec, exec, s[4:5]
	v_mov_b32_e32 v0, s48
	s_waitcnt lgkmcnt(0)
	s_barrier
	ds_read_b32 v0, v0
	s_mov_b64 s[4:5], -1
	s_waitcnt lgkmcnt(0)
	v_cmp_lt_i32_e32 vcc, 63, v0
	v_readfirstlane_b32 s6, v0
	s_cbranch_vccnz .LBB0_1101
	s_mov_b64 s[82:83], s[0:1]
	v_mov_b32_e32 v100, v226
	s_load_dwordx2 s[56:57], s[82:83], 0x58
	s_lshl_b32 s5, s6, 1
	s_and_b32 s4, s6, 1
	s_and_b32 s5, s5, -4
	s_sub_i32 s5, 0x7c, s5
	s_or_b32 s6, s4, s38
	s_waitcnt lgkmcnt(0)
	s_add_u32 s80, s56, 0xb400000
	v_readfirstlane_b32 s4, v100
	s_addc_u32 s81, s57, 0
	s_ashr_i32 s7, s4, 8
	s_lshl_b32 s22, s6, 1
	s_bfe_u32 s9, s5, 0x50002
	s_add_i32 s8, s7, s22
	s_lshl_b32 s5, s5, 4
	v_and_b32_e32 v28, 15, v100
	s_or_b32 s5, s5, s39
	s_lshr_b32 s4, s4, 2
	s_lshl_b32 s8, s8, 7
	s_and_b32 s23, s5, 0xfffff800
	s_lshl_b32 s5, s9, 6
	v_and_or_b32 v127, s4, 48, v28
	s_add_i32 s4, s8, 0x800
	s_or_b32 s5, s5, s23
	s_ashr_i32 s4, s4, 7
	v_or_b32_e32 v96, s5, v127
	s_ashr_i32 s5, s4, 31
	s_lshl_b64 s[4:5], s[4:5], 21
	v_ashrrev_i32_e32 v18, 5, v100
	v_ashrrev_i32_e32 v97, 31, v96
	s_add_u32 s4, s80, s4
	v_add_u32_e32 v16, s23, v18
	v_bfe_u32 v29, v100, 4, 2
	s_addc_u32 s5, s81, s5
	v_lshlrev_b64 v[98:99], 8, v[96:97]
	v_ashrrev_i32_e32 v17, 31, v16
	v_lshl_add_u64 v[0:1], s[4:5], 0, v[98:99]
	v_lshlrev_b32_e32 v208, 4, v29
	v_and_b32_e32 v19, 16, v100
	v_lshlrev_b64 v[16:17], 8, v[16:17]
	s_lshl_b32 s4, s6, 22
	v_lshl_add_u64 v[12:13], v[0:1], 0, v[208:209]
	v_lshl_add_u64 v[16:17], s[80:81], 0, v[16:17]
	v_lshl_or_b32 v208, v19, 17, s4
	v_lshlrev_b32_e32 v19, 4, v100
	v_lshl_add_u64 v[16:17], v[16:17], 0, v[208:209]
	v_and_b32_e32 v208, 0xf0, v19
	v_lshl_add_u64 v[16:17], v[16:17], 0, v[208:209]
	v_ashrrev_i32_e32 v19, 3, v100
	s_ashr_i32 s4, s23, 6
	v_lshl_add_u64 v[102:103], v[16:17], 0, s[62:63]
	v_lshl_add_u32 v16, s6, 8, v19
	s_ashr_i32 s5, s4, 31
	v_add_u32_e32 v16, 0x400, v16
	s_lshl_b64 s[4:5], s[4:5], 18
	v_lshlrev_b32_e32 v21, 3, v100
	v_ashrrev_i32_e32 v17, 31, v16
	s_add_u32 s4, s56, s4
	v_and_b32_e32 v22, 56, v21
	s_addc_u32 s5, s57, s5
	v_lshlrev_b64 v[16:17], 7, v[16:17]
	v_lshl_add_u64 v[16:17], s[4:5], 0, v[16:17]
	v_lshlrev_b32_e32 v208, 1, v22
	v_lshl_add_u64 v[16:17], v[16:17], 0, v[208:209]
	v_lshl_add_u64 v[104:105], v[16:17], 0, s[64:65]
	v_mul_lo_u32 v16, v19, s49
	v_add_lshl_u32 v31, v16, v22, 1
	v_lshlrev_b32_e32 v16, 2, v100
	v_sub_u32_e64 v20, s9, 8 clamp
	v_and_b32_e32 v16, 64, v16
	v_add_u32_e32 v16, v16, v18
	v_lshlrev_b32_e32 v208, 18, v20
	v_mul_lo_u32 v56, v16, s28
	v_lshl_add_u64 v[16:17], v[104:105], 0, v[208:209]
	v_add_co_u32_e32 v18, vcc, s21, v16
	v_lshlrev_b32_e32 v208, 14, v20
	v_readfirstlane_b32 s40, v20
	v_and_b32_e32 v57, 0x78, v21
	v_addc_co_u32_e32 v19, vcc, 0, v17, vcc
	v_lshl_add_u64 v[20:21], v[102:103], 0, v[208:209]
	v_add_co_u32_e32 v22, vcc, s35, v20
	global_load_dwordx4 v[0:3], v[12:13], off
	global_load_dwordx4 v[4:7], v[12:13], off offset:64
	global_load_dwordx4 v[8:11], v[12:13], off offset:128
	s_nop 0
	global_load_dwordx4 v[12:15], v[12:13], off offset:192
	v_addc_co_u32_e32 v23, vcc, 0, v21, vcc
	v_add_co_u32_e32 v24, vcc, s20, v16
	s_mul_i32 s4, s7, 0x410
	s_nop 0
	v_addc_co_u32_e32 v25, vcc, 0, v17, vcc
	v_add_co_u32_e32 v26, vcc, s17, v20
	s_add_i32 s41, s4, 0
	s_nop 0
	v_addc_co_u32_e32 v27, vcc, 0, v21, vcc
	global_load_dwordx4 v[52:55], v[24:25], off
	global_load_dwordx4 v[48:51], v[26:27], off
	v_add_co_u32_e32 v24, vcc, s17, v16
	v_lshlrev_b32_e32 v30, 3, v29
	s_nop 0
	v_addc_co_u32_e32 v25, vcc, 0, v17, vcc
	v_add_co_u32_e32 v26, vcc, s34, v20
	s_or_b32 s84, s12, s22
	s_nop 0
	v_addc_co_u32_e32 v27, vcc, 0, v21, vcc
	global_load_dwordx4 v[44:47], v[24:25], off
	global_load_dwordx4 v[40:43], v[26:27], off
	global_load_dwordx4 v[64:67], v[18:19], off
	global_load_dwordx4 v[32:35], v[16:17], off
	global_load_dwordx4 v[60:63], v[22:23], off
	global_load_dwordx4 v[36:39], v[20:21], off
	v_and_b32_e32 v19, 64, v233
	v_xor_b32_e32 v18, 16, v233
	v_add_u32_e32 v19, 64, v19
	v_cmp_lt_i32_e64 s[4:5], v18, v19
	v_max_i32_e32 v20, 2, v100
	v_sub_u32_e32 v20, v20, v100
	v_cndmask_b32_e64 v18, v233, v18, s[4:5]
	v_lshlrev_b32_e32 v126, 2, v18
	v_xor_b32_e32 v18, 32, v233
	v_cmp_lt_i32_e64 s[4:5], v18, v19
	v_add_u32_e32 v20, 0x1ff, v20
	v_lshl_or_b32 v17, s7, 6, v28
	v_cndmask_b32_e64 v18, v233, v18, s[4:5]
	v_lshrrev_b32_e32 v21, 9, v20
	v_mul_lo_u32 v17, v17, s28
	v_lshlrev_b32_e32 v125, 2, v18
	v_lshl_or_b32 v18, s7, 7, v28
	v_add_u32_e32 v21, 1, v21
	v_add_lshl_u32 v16, v56, v57, 1
	v_cmp_lt_i32_e32 vcc, s24, v100
	v_add_lshl_u32 v17, v17, v30, 1
	v_mul_lo_u32 v18, v18, s16
	v_add_u32_e32 v19, 0, v30
	v_lshlrev_b32_e32 v208, 2, v29
	v_and_b32_e32 v129, 0xfffffe, v21
	v_mov_b32_e32 v135, 0
	s_mov_b32 s43, s76
	s_add_i32 s41, s41, 0x23000
	s_mov_b32 s85, s13
	v_not_b32_e32 v128, v208
	v_or_b32_e32 v124, 16, v208
	v_or_b32_e32 v123, 32, v208
	v_or_b32_e32 v122, 48, v208
	v_cmp_lt_u32_e64 s[4:5], s61, v20
	v_lshl_add_u32 v130, v129, 9, v100
	s_mov_b32 s86, s84
	s_mov_b32 s87, s13
	s_mov_b32 s88, s84
	s_mov_b32 s89, s13
	v_add_u32_e32 v101, 0x200, v100
	v_cmp_ne_u32_e64 s[6:7], v21, v129
	v_mov_b32_e32 v136, 0xf149f2ca
	v_add_u32_e32 v131, 0, v16
	v_add_u32_e32 v132, 0, v31
	s_xor_b64 s[90:91], vcc, -1
	v_add_u32_e32 v133, 0, v17
	v_add_u32_e32 v134, v19, v18
	v_and_b32_e32 v149, 15, v100
	v_add_u32_e32 v149, 4, v149
	v_bfe_u32 v149, v149, 3, 1
	v_bfe_u32 v150, v100, 4, 2
	v_xor_b32_e32 v151, v150, v149
	v_lshlrev_b32_e32 v151, 4, v151
	v_lshlrev_b32_e32 v150, 3, v150
	v_sub_u32_e32 v151, v151, v150
	v_add_u32_e32 v134, v134, v151
	v_and_b32_e32 v149, 7, v100
	v_lshlrev_b32_e32 v150, 4, v149
	v_sub_u32_e32 v132, v132, v150
	v_and_b32_e32 v150, 4, v149
	v_lshl_add_u32 v132, v150, 4, v132
	v_and_b32_e32 v150, 1, v149
	v_lshl_add_u32 v132, v150, 5, v132
	v_and_b32_e32 v150, 2, v149
	v_lshl_add_u32 v132, v150, 2, v132
	v_bfe_u32 v150, v100, 3, 4
	v_add_u32_e32 v150, 4, v150
	v_bfe_u32 v150, v150, 3, 1
	v_lshlrev_b32_e32 v150, 4, v150
	v_sub_u32_e32 v148, 16, v150
	v_add_u32_e32 v148, v148, v132
	v_add_u32_e32 v132, v132, v150
	s_mov_b32 s32, 0x11800
	s_mov_b32 s42, s40
	v_mov_b32_e32 v20, 0
	v_mov_b32_e32 v21, v135
	v_mov_b32_e32 v22, v135
	v_mov_b32_e32 v23, v135
	v_mov_b32_e32 v28, 0
	v_mov_b32_e32 v29, v135
	v_mov_b32_e32 v30, v135
	v_mov_b32_e32 v31, v135
	v_mov_b32_e32 v16, 0
	v_mov_b32_e32 v17, v135
	v_mov_b32_e32 v18, v135
	v_mov_b32_e32 v19, v135
	v_mov_b32_e32 v56, 0
	v_mov_b32_e32 v57, v135
	v_mov_b32_e32 v58, v135
	v_mov_b32_e32 v59, v135
	v_mov_b32_e32 v68, 0
	v_mov_b32_e32 v69, v135
	v_mov_b32_e32 v70, v135
	v_mov_b32_e32 v71, v135
	v_mov_b32_e32 v72, 0
	v_mov_b32_e32 v73, v135
	v_mov_b32_e32 v74, v135
	v_mov_b32_e32 v75, v135
	v_mov_b32_e32 v24, 0
	v_mov_b32_e32 v25, v135
	v_mov_b32_e32 v26, v135
	v_mov_b32_e32 v27, v135
	v_mov_b32_e32 v76, 0
	v_mov_b32_e32 v77, v135
	v_mov_b32_e32 v78, v135
	v_mov_b32_e32 v79, v135
.LBB0_1110:
	s_cmp_eq_u32 s42, s40
	s_cselect_b64 s[22:23], -1, 0
	s_and_b64 s[22:23], s[90:91], s[22:23]
	s_waitcnt vmcnt(0)
	ds_write_b128 v131, v[36:39]
	ds_write_b64 v132, v[32:33] offset:34816
	ds_write_b64 v148, v[34:35] offset:34816
	ds_write_b128 v131, v[40:43] offset:4352
	ds_write_b64 v132, v[44:45] offset:44032
	ds_write_b64 v148, v[46:47] offset:44032
	ds_write_b128 v131, v[48:51] offset:8704
	ds_write_b64 v132, v[52:53] offset:53248
	ds_write_b64 v148, v[54:55] offset:53248
	ds_write_b128 v131, v[60:63] offset:13056
	ds_write_b64 v132, v[64:65] offset:62464
	ds_write_b64 v148, v[66:67] offset:62464
	s_and_saveexec_b64 s[76:77], s[22:23]
	s_cbranch_execz .LBB0_1118
	s_load_dwordx2 s[92:93], s[82:83], 0x48
	s_mov_b64 s[22:23], -1
	v_mov_b32_e32 v80, v100
	s_and_saveexec_b64 s[94:95], s[4:5]
	s_cbranch_execz .LBB0_1115
	s_mov_b64 s[96:97], 0
	v_mov_b32_e32 v82, v129
	v_mov_b64_e32 v[80:81], v[100:101]

.LBB0_1124:
	s_nop 1
	ds_bpermute_b32 v80, v126, v137
	v_max_f32_e32 v81, v137, v137
	s_waitcnt lgkmcnt(0)
	v_max_f32_e32 v80, v80, v80
	v_max_f32_e32 v80, v81, v80
	ds_bpermute_b32 v81, v125, v80
	s_waitcnt lgkmcnt(0)
	v_max3_f32 v88, v136, v80, v81
	v_sub_f32_e32 v80, v136, v88
	v_exp_f32_e32 v90, v80
	v_sub_f32_e32 v80, v120, v88
	v_exp_f32_e32 v80, v80
	v_sub_f32_e32 v82, v121, v88
	v_exp_f32_e32 v82, v82
	v_sub_f32_e32 v83, v112, v88
	v_exp_f32_e32 v83, v83
	v_sub_f32_e32 v84, v113, v88
	v_exp_f32_e32 v84, v84
	v_sub_f32_e32 v85, v108, v88
	v_fma_f32 v81, v135, v90, v80
	v_exp_f32_e32 v85, v85
	v_sub_f32_e32 v86, v109, v88
	v_add_f32_e32 v81, v82, v81
	v_exp_f32_e32 v86, v86
	v_sub_f32_e32 v87, v106, v88
	v_add_f32_e32 v81, v83, v81
	v_exp_f32_e32 v87, v87
	v_sub_f32_e32 v89, v107, v88
	v_add_f32_e32 v81, v84, v81
	v_exp_f32_e32 v89, v89
	v_add_f32_e32 v81, v85, v81
	v_add_f32_e32 v81, v86, v81
	v_add_f32_e32 v81, v87, v81
	v_add_f32_e32 v91, v89, v81
	v_cvt_pk_bf16_f32 v81, v83, v84
	v_sub_f32_e32 v84, v110, v88
	v_cvt_pk_bf16_f32 v83, v87, v89
	v_exp_f32_e32 v89, v84
	v_sub_f32_e32 v84, v111, v88
	v_exp_f32_e32 v92, v84
	v_sub_f32_e32 v84, v114, v88
	v_exp_f32_e32 v93, v84
	v_sub_f32_e32 v84, v115, v88
	v_exp_f32_e32 v94, v84
	v_sub_f32_e32 v84, v116, v88
	v_exp_f32_e32 v95, v84
	v_sub_f32_e32 v84, v117, v88
	v_exp_f32_e32 v106, v84
	v_sub_f32_e32 v84, v118, v88
	v_exp_f32_e32 v107, v84
	v_sub_f32_e32 v84, v119, v88
	v_exp_f32_e32 v135, v84
	v_cvt_pk_bf16_f32 v84, v89, v92
	v_add_f32_e32 v89, v89, v91
	v_add_f32_e32 v89, v92, v89
	v_add_f32_e32 v89, v93, v89
	v_add_f32_e32 v89, v94, v89
	v_add_f32_e32 v89, v95, v89
	v_cvt_pk_bf16_f32 v80, v80, v82
	v_cvt_pk_bf16_f32 v82, v85, v86
	v_cvt_pk_bf16_f32 v85, v93, v94
	v_add_f32_e32 v89, v106, v89
	v_add_u32_e32 v94, 0x8800, v134
	v_cvt_pk_bf16_f32 v86, v95, v106
	v_cvt_pk_bf16_f32 v87, v107, v135
	v_pk_mul_f32 v[74:75], v[74:75], v[90:91] op_sel_hi:[1,0]
	v_pk_mul_f32 v[72:73], v[72:73], v[90:91] op_sel_hi:[1,0]
	v_pk_mul_f32 v[70:71], v[70:71], v[90:91] op_sel_hi:[1,0]
	v_pk_mul_f32 v[68:69], v[68:69], v[90:91] op_sel_hi:[1,0]
	v_pk_mul_f32 v[58:59], v[58:59], v[90:91] op_sel_hi:[1,0]
	v_pk_mul_f32 v[56:57], v[56:57], v[90:91] op_sel_hi:[1,0]
	v_pk_mul_f32 v[18:19], v[18:19], v[90:91] op_sel_hi:[1,0]
	v_pk_mul_f32 v[16:17], v[16:17], v[90:91] op_sel_hi:[1,0]
	v_pk_mul_f32 v[30:31], v[30:31], v[90:91] op_sel_hi:[1,0]
	v_pk_mul_f32 v[28:29], v[28:29], v[90:91] op_sel_hi:[1,0]
	v_pk_mul_f32 v[22:23], v[22:23], v[90:91] op_sel_hi:[1,0]
	v_pk_mul_f32 v[20:21], v[20:21], v[90:91] op_sel_hi:[1,0]
	v_pk_mul_f32 v[26:27], v[26:27], v[90:91] op_sel_hi:[1,0]
	v_pk_mul_f32 v[24:25], v[24:25], v[90:91] op_sel_hi:[1,0]
	v_pk_mul_f32 v[78:79], v[78:79], v[90:91] op_sel_hi:[1,0]
	v_pk_mul_f32 v[76:77], v[76:77], v[90:91] op_sel_hi:[1,0]
	v_add_f32_e32 v89, v107, v89
	ds_read_b128 v[90:93], v94
	ds_read_b128 v[106:109], v94 offset:64
	v_add_u32_e32 v94, 0x9000, v134
	ds_read_b128 v[110:113], v94 offset:256
	ds_read_b128 v[114:117], v94 offset:320
	v_add_u32_e32 v94, 0x9800, v134
	ds_read_b128 v[118:121], v94 offset:512
	ds_read_b128 v[136:139], v94 offset:576
	v_add_u32_e32 v94, 0xa000, v134
	ds_read_b128 v[140:143], v94 offset:768
	ds_read_b128 v[144:147], v94 offset:832
	s_waitcnt lgkmcnt(7)
	v_mfma_f32_16x16x32_bf16 v[72:75], v[90:93], v[80:83], v[72:75]
	s_waitcnt lgkmcnt(5)
	v_mfma_f32_16x16x32_bf16 v[68:71], v[110:113], v[80:83], v[68:71]
	s_waitcnt lgkmcnt(3)
	v_mfma_f32_16x16x32_bf16 v[56:59], v[118:121], v[80:83], v[56:59]
	s_waitcnt lgkmcnt(1)
	v_mfma_f32_16x16x32_bf16 v[16:19], v[140:143], v[80:83], v[16:19]
	v_mfma_f32_16x16x32_bf16 v[72:75], v[106:109], v[84:87], v[72:75]
	v_mfma_f32_16x16x32_bf16 v[68:71], v[114:117], v[84:87], v[68:71]
	v_mfma_f32_16x16x32_bf16 v[56:59], v[136:139], v[84:87], v[56:59]
	s_waitcnt lgkmcnt(0)
	v_mfma_f32_16x16x32_bf16 v[16:19], v[144:147], v[84:87], v[16:19]
	v_add_u32_e32 v94, 0xa800, v134
	ds_read_b128 v[90:93], v94 offset:1024
	ds_read_b128 v[106:109], v94 offset:1088
	v_add_u32_e32 v94, 0xb000, v134
	ds_read_b128 v[110:113], v94 offset:1280
	ds_read_b128 v[114:117], v94 offset:1344
	v_add_u32_e32 v94, 0xb800, v134
	ds_read_b128 v[118:121], v94 offset:1536
	ds_read_b128 v[136:139], v94 offset:1600
	v_add_u32_e32 v94, 0xc000, v134
	ds_read_b128 v[140:143], v94 offset:1792
	ds_read_b128 v[144:147], v94 offset:1856
	s_waitcnt lgkmcnt(7)
	v_mfma_f32_16x16x32_bf16 v[28:31], v[90:93], v[80:83], v[28:31]
	s_waitcnt lgkmcnt(5)
	v_mfma_f32_16x16x32_bf16 v[20:23], v[110:113], v[80:83], v[20:23]
	s_waitcnt lgkmcnt(3)
	v_mfma_f32_16x16x32_bf16 v[24:27], v[118:121], v[80:83], v[24:27]
	s_waitcnt lgkmcnt(1)
	v_mfma_f32_16x16x32_bf16 v[76:79], v[140:143], v[80:83], v[76:79]
	v_mfma_f32_16x16x32_bf16 v[28:31], v[106:109], v[84:87], v[28:31]
	v_mfma_f32_16x16x32_bf16 v[20:23], v[114:117], v[84:87], v[20:23]
	v_mfma_f32_16x16x32_bf16 v[24:27], v[136:139], v[84:87], v[24:27]
	s_waitcnt lgkmcnt(0)
	v_mfma_f32_16x16x32_bf16 v[76:79], v[144:147], v[84:87], v[76:79]
	v_add_f32_e32 v135, v135, v89
	s_andn2_b64 vcc, exec, s[76:77]
	s_add_i32 s42, s42, 1
	s_cbranch_vccz .LBB0_1100
	v_mov_b32_e32 v136, v88
	v_add_u32_e32 v131, s32, v131
	v_add_u32_e32 v132, s32, v132
	v_add_u32_e32 v148, s32, v148
	v_add_u32_e32 v133, s32, v133
	v_add_u32_e32 v134, s32, v134
	s_sub_i32 s32, 0, s32
	s_branch .LBB0_1110
